# prep T items: rotary table entries fetched once per thread and reused by the five GQA q/k iterations instead of re-loaded each time
# speedup vs baseline: 1.0076x; 1.0014x over previous
.LBB0_490:
	s_waitcnt vmcnt(0)
	v_cvt_pk_bf16_f32 v6, v6, v7
	v_cvt_pk_bf16_f32 v5, v4, v5
	v_cvt_pk_bf16_f32 v4, v2, v3
	s_mov_b64 s[4:5], 0x1e00
	global_store_dwordx3 v[26:27], v[4:6], off offset:4
	v_mov_b32_e32 v15, v129
	v_and_b32_e32 v0, 2, v120
	v_lshl_add_u64 v[6:7], v[16:17], 0, s[4:5]
	v_lshl_add_u64 v[8:9], v[6:7], 0, v[14:15]
	v_cmp_eq_u32_e64 s[40:41], 0, v0
	global_load_dwordx4 v[0:3], v[8:9], off offset:16
	s_nop 0
	global_load_dwordx4 v[8:11], v[8:9], off
	v_and_b32_e32 v34, 56, v40
	v_readlane_b32 s4, v238, 42
	v_lshlrev_b32_e32 v4, 2, v34
	v_readlane_b32 s5, v238, 43
	s_nop 4
	global_load_dwordx4 v[24:27], v4, s[4:5] offset:16
	global_load_dwordx4 v[28:31], v4, s[4:5]
	v_ashrrev_i32_e32 v35, 6, v12
	v_and_b32_e32 v36, 63, v12
	v_cmp_gt_u32_e64 s[42:43], 32, v34
	v_and_b32_e32 v37, 8, v40
	s_waitcnt vmcnt(3)
	v_pk_mul_f32 v[48:49], v[0:1], v[0:1]
	s_waitcnt vmcnt(2)
	v_pk_mul_f32 v[38:39], v[8:9], v[8:9]
	v_pk_mul_f32 v[46:47], v[10:11], v[10:11]
	v_add_f32_e32 v5, v38, v39
	v_add_f32_e32 v5, v5, v46
	v_add_f32_e32 v5, v5, v47
	v_add_f32_e32 v5, v5, v48
	v_pk_mul_f32 v[32:33], v[2:3], v[2:3]
	v_add_f32_e32 v5, v5, v49
	v_add_f32_e32 v5, v5, v32
	v_add_f32_e32 v5, v5, v33
	s_nop 1
	v_add_f32_dpp v5, v5, v5 quad_perm:[1,0,3,2] row_mask:0xf bank_mask:0xf bound_ctrl:1
	s_nop 1
	v_add_f32_dpp v5, v5, v5 quad_perm:[2,3,0,1] row_mask:0xf bank_mask:0xf bound_ctrl:1
	s_nop 1
	v_add_f32_dpp v5, v5, v5 row_half_mirror row_mask:0xf bank_mask:0xf bound_ctrl:1
	v_fmamk_f32 v5, v5, 0x3c800000, v179
	v_cmp_gt_f32_e32 vcc, s60, v5
	v_mul_f32_e32 v15, 0x4b800000, v5
	s_nop 0
	v_cndmask_b32_e32 v5, v5, v15, vcc
	v_rsq_f32_e32 v5, v5
	s_nop 0
	v_mul_f32_e32 v15, 0x45800000, v5
	v_cndmask_b32_e32 v38, v5, v15, vcc
	v_pk_mul_f32 v[8:9], v[8:9], v[38:39] op_sel_hi:[1,0]
	v_pk_mul_f32 v[0:1], v[0:1], v[38:39] op_sel_hi:[1,0]
	s_waitcnt vmcnt(0)
	v_pk_mul_f32 v[32:33], v[28:29], v[8:9]
	v_pk_mul_f32 v[8:9], v[10:11], v[38:39] op_sel_hi:[1,0]
	v_pk_mul_f32 v[10:11], v[24:25], v[0:1]
	v_pk_mul_f32 v[0:1], v[2:3], v[38:39] op_sel_hi:[1,0]
	v_pk_mul_f32 v[30:31], v[30:31], v[8:9]
	v_pk_mul_f32 v[8:9], v[26:27], v[0:1]
	s_and_b64 vcc, exec, s[38:39]
	s_cbranch_vccnz .LBB0_492
	v_cndmask_b32_e64 v0, v36, v35, s[42:43]
	v_lshl_or_b32 v0, v0, 4, v37
	v_readlane_b32 s4, v242, 21
	v_ashrrev_i32_e32 v1, 31, v0
	v_readlane_b32 s6, v242, 23
	v_readlane_b32 s7, v242, 24
	v_mov_b32_e32 v5, v129
	v_mov_b32_e32 v39, v33
	v_lshl_add_u64 v[24:25], v[0:1], 3, s[6:7]
	global_load_dwordx4 v[0:3], v[24:25], off offset:48
	global_load_dwordx4 v[46:49], v[24:25], off offset:32
	global_load_dwordx4 v[50:53], v[24:25], off offset:16
	global_load_dwordx4 v[54:57], v[24:25], off
	global_load_dwordx4 v[204:207], v[24:25], off offset:48
	global_load_dwordx4 v[208:211], v[24:25], off offset:32
	global_load_dwordx4 v[212:215], v[24:25], off offset:16
	global_load_dwordx4 v[216:219], v[24:25], off
	v_mov_b32_dpp v5, v32 quad_perm:[2,3,0,1] row_mask:0xf bank_mask:0xf
	v_cndmask_b32_e64 v38, v5, -v5, s[40:41]
	v_mov_b32_e32 v5, v129
	v_readlane_b32 s5, v242, 22
	s_waitcnt vmcnt(3)
	v_mul_f32_e32 v0, v8, v0
	v_mov_b32_dpp v5, v33 quad_perm:[2,3,0,1] row_mask:0xf bank_mask:0xf
	v_cndmask_b32_e64 v5, v5, -v5, s[40:41]
	v_mov_b32_e32 v33, v5
	v_mov_b32_e32 v5, v129
	s_waitcnt vmcnt(0)
	v_mov_b32_e32 v24, v55
	v_mov_b32_e32 v55, v57
	v_mov_b32_dpp v5, v30 quad_perm:[2,3,0,1] row_mask:0xf bank_mask:0xf
	v_pk_mul_f32 v[32:33], v[32:33], v[54:55]
	v_cndmask_b32_e64 v54, v5, -v5, s[40:41]
	v_mov_b32_e32 v5, v129
	v_mov_b32_e32 v55, v31
	v_mov_b32_e32 v26, v51
	v_mov_b32_dpp v5, v31 quad_perm:[2,3,0,1] row_mask:0xf bank_mask:0xf
	v_cndmask_b32_e64 v5, v5, -v5, s[40:41]
	v_mov_b32_e32 v31, v5
	v_mov_b32_e32 v5, v129
	v_mov_b32_e32 v51, v53
	v_pk_mul_f32 v[30:31], v[30:31], v[50:51]
	v_mov_b32_dpp v5, v10 quad_perm:[2,3,0,1] row_mask:0xf bank_mask:0xf
	v_cndmask_b32_e64 v50, v5, -v5, s[40:41]
	v_mov_b32_e32 v5, v129
	v_mov_b32_e32 v51, v11
	v_mov_b32_e32 v28, v47
	v_mov_b32_dpp v5, v11 quad_perm:[2,3,0,1] row_mask:0xf bank_mask:0xf
	v_cndmask_b32_e64 v5, v5, -v5, s[40:41]
	v_mov_b32_e32 v11, v5
	v_mov_b32_e32 v5, v129
	v_mov_b32_e32 v47, v49
	v_pk_mul_f32 v[10:11], v[10:11], v[46:47]
	v_mov_b32_dpp v5, v8 quad_perm:[2,3,0,1] row_mask:0xf bank_mask:0xf
	v_cndmask_b32_e64 v5, v5, -v5, s[40:41]
	v_mul_f32_e32 v8, v1, v5
	v_mov_b32_e32 v1, v129
	v_mov_b32_e32 v46, v9
	v_mov_b32_e32 v25, v56
	v_mov_b32_dpp v1, v9 quad_perm:[2,3,0,1] row_mask:0xf bank_mask:0xf
	v_cndmask_b32_e64 v47, v1, -v1, s[40:41]
	v_pk_mul_f32 v[2:3], v[46:47], v[2:3]
	v_mov_b32_e32 v27, v52
	v_mov_b32_e32 v29, v48
	v_mov_b32_e32 v1, v2
	v_mov_b32_e32 v9, v3
	v_pk_fma_f32 v[32:33], v[24:25], v[38:39], v[32:33]
	v_pk_fma_f32 v[30:31], v[26:27], v[54:55], v[30:31]
	v_pk_fma_f32 v[10:11], v[28:29], v[50:51], v[10:11]
	v_pk_add_f32 v[8:9], v[0:1], v[8:9]
.LBB0_492:
	v_readlane_b32 s68, v242, 41
	v_lshlrev_b64 v[18:19], 10, v[18:19]
	v_pk_mul_f32 v[0:1], v[32:33], s[10:11] op_sel_hi:[1,0]
	v_pk_mul_f32 v[2:3], v[30:31], s[10:11] op_sel_hi:[1,0]
	v_pk_mul_f32 v[8:9], v[8:9], s[10:11] op_sel_hi:[1,0]
	v_readlane_b32 s69, v242, 42
	v_readlane_b32 s70, v242, 43
	v_readlane_b32 s71, v242, 44
	v_readlane_b32 s72, v242, 45
	v_readlane_b32 s73, v242, 46
	v_readlane_b32 s74, v242, 47
	v_readlane_b32 s75, v242, 48
	v_readlane_b32 s76, v242, 49
	v_readlane_b32 s77, v242, 50
	v_readlane_b32 s78, v242, 51
	v_readlane_b32 s79, v242, 52
	v_readlane_b32 s80, v242, 53
	v_readlane_b32 s81, v242, 54
	v_readlane_b32 s82, v242, 55
	v_readlane_b32 s83, v242, 56
	v_cvt_pk_bf16_f32 v0, v0, v1
	v_cvt_pk_bf16_f32 v1, v2, v3
	v_cvt_pk_bf16_f32 v3, v8, v9
	v_lshl_add_u64 v[8:9], s[82:83], 0, v[18:19]
	v_readlane_b32 s68, v242, 57
	v_lshlrev_b64 v[20:21], 10, v[20:21]
	v_pk_mul_f32 v[10:11], v[10:11], s[10:11] op_sel_hi:[1,0]
	v_readlane_b32 s78, v241, 3
	v_readlane_b32 s79, v241, 4
	v_cvt_pk_bf16_f32 v2, v10, v11
	v_mov_b32_e32 v23, v129
	v_lshl_add_u64 v[10:11], s[78:79], 0, v[20:21]
	v_cndmask_b32_e64 v9, v11, v9, s[62:63]
	v_cndmask_b32_e64 v8, v10, v8, s[62:63]
	v_lshl_add_u64 v[8:9], v[8:9], 0, v[22:23]
	global_store_dwordx4 v[8:9], v[0:3], off
	v_lshl_add_u64 v[10:11], v[6:7], 0, v[128:129]
	global_load_dwordx4 v[0:3], v[10:11], off offset:16
	global_load_dwordx4 v[18:21], v[10:11], off
	v_readlane_b32 s4, v238, 42
	v_mov_b32_e32 v5, v129
	v_readlane_b32 s5, v238, 43
	s_and_b64 vcc, exec, s[38:39]
	v_readlane_b32 s69, v242, 58
	v_lshl_add_u64 v[10:11], s[4:5], 0, v[4:5]
	global_load_dwordx4 v[22:25], v[10:11], off
	global_load_dwordx4 v[46:49], v[10:11], off offset:16
	v_readlane_b32 s70, v242, 59
	v_readlane_b32 s71, v242, 60
	v_readlane_b32 s72, v242, 61
	v_readlane_b32 s73, v242, 62
	v_readlane_b32 s74, v242, 63
	v_readlane_b32 s75, v241, 0
	v_readlane_b32 s76, v241, 1
	v_readlane_b32 s77, v241, 2
	v_readlane_b32 s80, v241, 5
	v_readlane_b32 s81, v241, 6
	v_readlane_b32 s82, v241, 7
	v_readlane_b32 s83, v241, 8
	s_waitcnt vmcnt(3)
	v_pk_mul_f32 v[32:33], v[0:1], v[0:1]
	s_waitcnt vmcnt(2)
	v_pk_mul_f32 v[28:29], v[18:19], v[18:19]
	v_pk_mul_f32 v[30:31], v[20:21], v[20:21]
	v_add_f32_e32 v5, v28, v29
	v_add_f32_e32 v5, v5, v30
	v_add_f32_e32 v5, v5, v31
	v_add_f32_e32 v5, v5, v32
	v_pk_mul_f32 v[26:27], v[2:3], v[2:3]
	v_add_f32_e32 v5, v5, v33
	v_add_f32_e32 v5, v5, v26
	v_add_f32_e32 v5, v5, v27
	s_nop 1
	v_add_f32_dpp v5, v5, v5 quad_perm:[1,0,3,2] row_mask:0xf bank_mask:0xf bound_ctrl:1
	s_nop 1
	v_add_f32_dpp v5, v5, v5 quad_perm:[2,3,0,1] row_mask:0xf bank_mask:0xf bound_ctrl:1
	s_nop 1
	v_add_f32_dpp v5, v5, v5 row_half_mirror row_mask:0xf bank_mask:0xf bound_ctrl:1
	v_fmamk_f32 v5, v5, 0x3c800000, v179
	v_mul_f32_e32 v15, 0x4b800000, v5
	v_cmp_gt_f32_e64 s[42:43], s60, v5
	s_nop 1
	v_cndmask_b32_e64 v5, v5, v15, s[42:43]
	v_rsq_f32_e32 v5, v5
	s_nop 0
	v_mul_f32_e32 v15, 0x45800000, v5
	v_cndmask_b32_e64 v26, v5, v15, s[42:43]
	v_pk_mul_f32 v[18:19], v[18:19], v[26:27] op_sel_hi:[1,0]
	v_pk_mul_f32 v[20:21], v[20:21], v[26:27] op_sel_hi:[1,0]
	v_pk_mul_f32 v[0:1], v[0:1], v[26:27] op_sel_hi:[1,0]
	v_pk_mul_f32 v[2:3], v[2:3], v[26:27] op_sel_hi:[1,0]
	s_waitcnt vmcnt(1)
	v_pk_mul_f32 v[30:31], v[22:23], v[18:19]
	v_pk_mul_f32 v[28:29], v[24:25], v[20:21]
	s_waitcnt vmcnt(0)
	v_pk_mul_f32 v[26:27], v[46:47], v[0:1]
	v_pk_mul_f32 v[24:25], v[48:49], v[2:3]
	s_cbranch_vccnz .LBB0_494
	v_cmp_gt_u32_e32 vcc, 32, v34
	v_readlane_b32 s4, v242, 21
	v_readlane_b32 s6, v242, 23
	v_cndmask_b32_e32 v0, v36, v35, vcc
	v_lshl_or_b32 v0, v0, 4, v37
	v_ashrrev_i32_e32 v1, 31, v0
	v_readlane_b32 s7, v242, 24
	v_mov_b32_e32 v5, v129
	v_mov_b32_e32 v33, v31
	v_lshl_add_u64 v[18:19], v[0:1], 3, s[6:7]
	v_mov_b64_e32 v[0:1], v[204:205]
	v_mov_b64_e32 v[2:3], v[206:207]
	v_mov_b64_e32 v[46:47], v[208:209]
	v_mov_b64_e32 v[48:49], v[210:211]
	v_mov_b64_e32 v[50:51], v[212:213]
	v_mov_b64_e32 v[52:53], v[214:215]
	v_mov_b64_e32 v[54:55], v[216:217]
	v_mov_b64_e32 v[56:57], v[218:219]
	v_mov_b32_dpp v5, v30 quad_perm:[2,3,0,1] row_mask:0xf bank_mask:0xf
	v_cndmask_b32_e64 v32, v5, -v5, s[40:41]
	v_mov_b32_e32 v5, v129
	v_mov_b32_e32 v39, v29
	v_readlane_b32 s5, v242, 22
	v_mov_b32_dpp v5, v31 quad_perm:[2,3,0,1] row_mask:0xf bank_mask:0xf
	v_cndmask_b32_e64 v5, v5, -v5, s[40:41]
	v_mov_b32_e32 v31, v5
	v_mov_b32_e32 v5, v129
	s_waitcnt vmcnt(3)
	v_mul_f32_e32 v0, v24, v0
	v_mov_b32_dpp v5, v28 quad_perm:[2,3,0,1] row_mask:0xf bank_mask:0xf
	v_cndmask_b32_e64 v38, v5, -v5, s[40:41]
	v_mov_b32_e32 v5, v129
	s_waitcnt vmcnt(1)
	v_mov_b32_e32 v20, v51
	v_mov_b32_e32 v51, v53
	v_mov_b32_dpp v5, v29 quad_perm:[2,3,0,1] row_mask:0xf bank_mask:0xf
	v_cndmask_b32_e64 v5, v5, -v5, s[40:41]
	v_mov_b32_e32 v29, v5
	v_mov_b32_e32 v5, v129
	v_pk_mul_f32 v[28:29], v[28:29], v[50:51]
	v_mov_b32_e32 v51, v27
	v_mov_b32_dpp v5, v26 quad_perm:[2,3,0,1] row_mask:0xf bank_mask:0xf
	v_cndmask_b32_e64 v50, v5, -v5, s[40:41]
	v_mov_b32_e32 v5, v129
	v_mov_b32_e32 v22, v47
	v_mov_b32_e32 v47, v49
	v_mov_b32_dpp v5, v27 quad_perm:[2,3,0,1] row_mask:0xf bank_mask:0xf
	v_cndmask_b32_e64 v5, v5, -v5, s[40:41]
	v_mov_b32_e32 v27, v5
	v_mov_b32_e32 v5, v129
	v_pk_mul_f32 v[26:27], v[26:27], v[46:47]
	v_mov_b32_e32 v46, v25
	v_mov_b32_dpp v5, v24 quad_perm:[2,3,0,1] row_mask:0xf bank_mask:0xf
	v_cndmask_b32_e64 v5, v5, -v5, s[40:41]
	v_mul_f32_e32 v24, v1, v5
	v_mov_b32_e32 v1, v129
	s_waitcnt vmcnt(0)
	v_mov_b32_e32 v18, v55
	v_mov_b32_e32 v55, v57
	v_mov_b32_dpp v1, v25 quad_perm:[2,3,0,1] row_mask:0xf bank_mask:0xf
	v_cndmask_b32_e64 v47, v1, -v1, s[40:41]
	v_pk_mul_f32 v[2:3], v[46:47], v[2:3]
	v_mov_b32_e32 v19, v56
	v_mov_b32_e32 v21, v52
	v_mov_b32_e32 v23, v48
	v_pk_mul_f32 v[30:31], v[30:31], v[54:55]
	v_mov_b32_e32 v1, v2
	v_mov_b32_e32 v25, v3
	v_pk_fma_f32 v[30:31], v[18:19], v[32:33], v[30:31]
	v_pk_fma_f32 v[28:29], v[20:21], v[38:39], v[28:29]
	v_pk_fma_f32 v[26:27], v[22:23], v[50:51], v[26:27]
	v_pk_add_f32 v[24:25], v[0:1], v[24:25]
.LBB0_494:
	v_pk_mul_f32 v[0:1], v[30:31], s[10:11] op_sel_hi:[1,0]
	v_pk_mul_f32 v[2:3], v[28:29], s[10:11] op_sel_hi:[1,0]
	v_pk_mul_f32 v[18:19], v[26:27], s[10:11] op_sel_hi:[1,0]
	v_pk_mul_f32 v[20:21], v[24:25], s[10:11] op_sel_hi:[1,0]
	v_cvt_pk_bf16_f32 v0, v0, v1
	v_cvt_pk_bf16_f32 v1, v2, v3
	v_cvt_pk_bf16_f32 v2, v18, v19
	v_cvt_pk_bf16_f32 v3, v20, v21
	v_lshl_or_b32 v128, v40, 2, v193
	global_store_dwordx4 v[8:9], v[0:3], off offset:256
	v_lshl_add_u64 v[18:19], v[6:7], 0, v[128:129]
	global_load_dwordx4 v[0:3], v[18:19], off offset:16
	s_nop 0
	global_load_dwordx4 v[18:21], v[18:19], off
	s_nop 0
	global_load_dwordx4 v[22:25], v[10:11], off
	global_load_dwordx4 v[46:49], v[10:11], off offset:16
	s_and_b64 vcc, exec, s[38:39]
	s_waitcnt vmcnt(3)
	v_pk_mul_f32 v[32:33], v[0:1], v[0:1]
	s_waitcnt vmcnt(2)
	v_pk_mul_f32 v[28:29], v[18:19], v[18:19]
	v_pk_mul_f32 v[30:31], v[20:21], v[20:21]
	v_add_f32_e32 v5, v28, v29
	v_add_f32_e32 v5, v5, v30
	v_add_f32_e32 v5, v5, v31
	v_add_f32_e32 v5, v5, v32
	v_pk_mul_f32 v[26:27], v[2:3], v[2:3]
	v_add_f32_e32 v5, v5, v33
	v_add_f32_e32 v5, v5, v26
	v_add_f32_e32 v5, v5, v27
	s_nop 1
	v_add_f32_dpp v5, v5, v5 quad_perm:[1,0,3,2] row_mask:0xf bank_mask:0xf bound_ctrl:1
	s_nop 1
	v_add_f32_dpp v5, v5, v5 quad_perm:[2,3,0,1] row_mask:0xf bank_mask:0xf bound_ctrl:1
	s_nop 1
	v_add_f32_dpp v5, v5, v5 row_half_mirror row_mask:0xf bank_mask:0xf bound_ctrl:1
	v_fmamk_f32 v5, v5, 0x3c800000, v179
	v_mul_f32_e32 v15, 0x4b800000, v5
	v_cmp_gt_f32_e64 s[42:43], s60, v5
	s_nop 1
	v_cndmask_b32_e64 v5, v5, v15, s[42:43]
	v_rsq_f32_e32 v5, v5
	s_nop 0
	v_mul_f32_e32 v15, 0x45800000, v5
	v_cndmask_b32_e64 v26, v5, v15, s[42:43]
	v_pk_mul_f32 v[18:19], v[18:19], v[26:27] op_sel_hi:[1,0]
	v_pk_mul_f32 v[20:21], v[20:21], v[26:27] op_sel_hi:[1,0]
	v_pk_mul_f32 v[0:1], v[0:1], v[26:27] op_sel_hi:[1,0]
	v_pk_mul_f32 v[2:3], v[2:3], v[26:27] op_sel_hi:[1,0]
	s_waitcnt vmcnt(1)
	v_pk_mul_f32 v[30:31], v[22:23], v[18:19]
	v_pk_mul_f32 v[28:29], v[24:25], v[20:21]
	s_waitcnt vmcnt(0)
	v_pk_mul_f32 v[26:27], v[46:47], v[0:1]
	v_pk_mul_f32 v[24:25], v[48:49], v[2:3]
	s_cbranch_vccnz .LBB0_496
	v_cmp_gt_u32_e32 vcc, 32, v34
	v_readlane_b32 s4, v242, 21
	v_readlane_b32 s6, v242, 23
	v_cndmask_b32_e32 v0, v36, v35, vcc
	v_lshl_or_b32 v0, v0, 4, v37
	v_ashrrev_i32_e32 v1, 31, v0
	v_readlane_b32 s7, v242, 24
	v_mov_b32_e32 v5, v129
	v_mov_b32_e32 v33, v31
	v_lshl_add_u64 v[18:19], v[0:1], 3, s[6:7]
	v_mov_b64_e32 v[0:1], v[204:205]
	v_mov_b64_e32 v[2:3], v[206:207]
	v_mov_b64_e32 v[46:47], v[208:209]
	v_mov_b64_e32 v[48:49], v[210:211]
	v_mov_b64_e32 v[50:51], v[212:213]
	v_mov_b64_e32 v[52:53], v[214:215]
	v_mov_b64_e32 v[54:55], v[216:217]
	v_mov_b64_e32 v[56:57], v[218:219]
	v_mov_b32_dpp v5, v30 quad_perm:[2,3,0,1] row_mask:0xf bank_mask:0xf
	v_cndmask_b32_e64 v32, v5, -v5, s[40:41]
	v_mov_b32_e32 v5, v129
	v_mov_b32_e32 v39, v29
	v_readlane_b32 s5, v242, 22
	v_mov_b32_dpp v5, v31 quad_perm:[2,3,0,1] row_mask:0xf bank_mask:0xf
	v_cndmask_b32_e64 v5, v5, -v5, s[40:41]
	v_mov_b32_e32 v31, v5
	v_mov_b32_e32 v5, v129
	s_waitcnt vmcnt(3)
	v_mul_f32_e32 v0, v24, v0
	v_mov_b32_dpp v5, v28 quad_perm:[2,3,0,1] row_mask:0xf bank_mask:0xf
	v_cndmask_b32_e64 v38, v5, -v5, s[40:41]
	v_mov_b32_e32 v5, v129
	s_waitcnt vmcnt(1)
	v_mov_b32_e32 v20, v51
	v_mov_b32_e32 v51, v53
	v_mov_b32_dpp v5, v29 quad_perm:[2,3,0,1] row_mask:0xf bank_mask:0xf
	v_cndmask_b32_e64 v5, v5, -v5, s[40:41]
	v_mov_b32_e32 v29, v5
	v_mov_b32_e32 v5, v129
	v_pk_mul_f32 v[28:29], v[28:29], v[50:51]
	v_mov_b32_e32 v51, v27
	v_mov_b32_dpp v5, v26 quad_perm:[2,3,0,1] row_mask:0xf bank_mask:0xf
	v_cndmask_b32_e64 v50, v5, -v5, s[40:41]
	v_mov_b32_e32 v5, v129
	v_mov_b32_e32 v22, v47
	v_mov_b32_e32 v47, v49
	v_mov_b32_dpp v5, v27 quad_perm:[2,3,0,1] row_mask:0xf bank_mask:0xf
	v_cndmask_b32_e64 v5, v5, -v5, s[40:41]
	v_mov_b32_e32 v27, v5
	v_mov_b32_e32 v5, v129
	v_pk_mul_f32 v[26:27], v[26:27], v[46:47]
	v_mov_b32_e32 v46, v25
	v_mov_b32_dpp v5, v24 quad_perm:[2,3,0,1] row_mask:0xf bank_mask:0xf
	v_cndmask_b32_e64 v5, v5, -v5, s[40:41]
	v_mul_f32_e32 v24, v1, v5
	v_mov_b32_e32 v1, v129
	s_waitcnt vmcnt(0)
	v_mov_b32_e32 v18, v55
	v_mov_b32_e32 v55, v57
	v_mov_b32_dpp v1, v25 quad_perm:[2,3,0,1] row_mask:0xf bank_mask:0xf
	v_cndmask_b32_e64 v47, v1, -v1, s[40:41]
	v_pk_mul_f32 v[2:3], v[46:47], v[2:3]
	v_mov_b32_e32 v19, v56
	v_mov_b32_e32 v21, v52
	v_mov_b32_e32 v23, v48
	v_pk_mul_f32 v[30:31], v[30:31], v[54:55]
	v_mov_b32_e32 v1, v2
	v_mov_b32_e32 v25, v3
	v_pk_fma_f32 v[30:31], v[18:19], v[32:33], v[30:31]
	v_pk_fma_f32 v[28:29], v[20:21], v[38:39], v[28:29]
	v_pk_fma_f32 v[26:27], v[22:23], v[50:51], v[26:27]
	v_pk_add_f32 v[24:25], v[0:1], v[24:25]
.LBB0_496:
	v_pk_mul_f32 v[0:1], v[30:31], s[10:11] op_sel_hi:[1,0]
	v_pk_mul_f32 v[2:3], v[28:29], s[10:11] op_sel_hi:[1,0]
	v_pk_mul_f32 v[18:19], v[26:27], s[10:11] op_sel_hi:[1,0]
	v_pk_mul_f32 v[20:21], v[24:25], s[10:11] op_sel_hi:[1,0]
	v_cvt_pk_bf16_f32 v0, v0, v1
	v_cvt_pk_bf16_f32 v1, v2, v3
	v_cvt_pk_bf16_f32 v2, v18, v19
	v_cvt_pk_bf16_f32 v3, v20, v21
	v_lshl_or_b32 v128, v40, 2, v194
	global_store_dwordx4 v[8:9], v[0:3], off offset:512
	v_lshl_add_u64 v[6:7], v[6:7], 0, v[128:129]
	global_load_dwordx4 v[0:3], v[6:7], off offset:16
	global_load_dwordx4 v[18:21], v[6:7], off
	global_load_dwordx4 v[22:25], v[10:11], off
	global_load_dwordx4 v[28:31], v[10:11], off offset:16
	s_and_b64 vcc, exec, s[38:39]
	s_waitcnt vmcnt(3)
	v_pk_mul_f32 v[32:33], v[0:1], v[0:1]
	s_waitcnt vmcnt(2)
	v_pk_mul_f32 v[10:11], v[18:19], v[18:19]
	v_pk_mul_f32 v[26:27], v[20:21], v[20:21]
	v_add_f32_e32 v5, v10, v11
	v_add_f32_e32 v5, v5, v26
	v_add_f32_e32 v5, v5, v27
	v_add_f32_e32 v5, v5, v32
	v_pk_mul_f32 v[6:7], v[2:3], v[2:3]
	v_add_f32_e32 v5, v5, v33
	v_add_f32_e32 v5, v5, v6
	v_add_f32_e32 v5, v5, v7
	s_nop 1
	v_add_f32_dpp v5, v5, v5 quad_perm:[1,0,3,2] row_mask:0xf bank_mask:0xf bound_ctrl:1
	s_nop 1
	v_add_f32_dpp v5, v5, v5 quad_perm:[2,3,0,1] row_mask:0xf bank_mask:0xf bound_ctrl:1
	s_nop 1
	v_add_f32_dpp v5, v5, v5 row_half_mirror row_mask:0xf bank_mask:0xf bound_ctrl:1
	v_fmamk_f32 v5, v5, 0x3c800000, v179
	v_mul_f32_e32 v6, 0x4b800000, v5
	v_cmp_gt_f32_e64 s[42:43], s60, v5
	s_nop 1
	v_cndmask_b32_e64 v5, v5, v6, s[42:43]
	v_rsq_f32_e32 v5, v5
	s_nop 0
	v_mul_f32_e32 v6, 0x45800000, v5
	v_cndmask_b32_e64 v6, v5, v6, s[42:43]
	v_pk_mul_f32 v[10:11], v[18:19], v[6:7] op_sel_hi:[1,0]
	v_pk_mul_f32 v[18:19], v[20:21], v[6:7] op_sel_hi:[1,0]
	v_pk_mul_f32 v[0:1], v[0:1], v[6:7] op_sel_hi:[1,0]
	v_pk_mul_f32 v[2:3], v[2:3], v[6:7] op_sel_hi:[1,0]
	s_waitcnt vmcnt(1)
	v_pk_mul_f32 v[26:27], v[22:23], v[10:11]
	v_pk_mul_f32 v[24:25], v[24:25], v[18:19]
	s_waitcnt vmcnt(0)
	v_pk_mul_f32 v[22:23], v[28:29], v[0:1]
	v_pk_mul_f32 v[20:21], v[30:31], v[2:3]
	s_cbranch_vccnz .LBB0_498
	v_cmp_gt_u32_e32 vcc, 32, v34
	v_readlane_b32 s4, v242, 21
	v_readlane_b32 s6, v242, 23
	v_cndmask_b32_e32 v0, v36, v35, vcc
	v_lshl_or_b32 v0, v0, 4, v37
	v_ashrrev_i32_e32 v1, 31, v0
	v_readlane_b32 s7, v242, 24
	v_mov_b32_e32 v5, v129
	v_mov_b32_e32 v33, v27
	v_lshl_add_u64 v[6:7], v[0:1], 3, s[6:7]
	v_mov_b64_e32 v[0:1], v[204:205]
	v_mov_b64_e32 v[2:3], v[206:207]
	v_mov_b64_e32 v[28:29], v[208:209]
	v_mov_b64_e32 v[30:31], v[210:211]
	v_mov_b64_e32 v[46:47], v[212:213]
	v_mov_b64_e32 v[48:49], v[214:215]
	v_mov_b64_e32 v[50:51], v[216:217]
	v_mov_b64_e32 v[52:53], v[218:219]
	v_mov_b32_dpp v5, v26 quad_perm:[2,3,0,1] row_mask:0xf bank_mask:0xf
	v_cndmask_b32_e64 v32, v5, -v5, s[40:41]
	v_mov_b32_e32 v5, v129
	v_mov_b32_e32 v39, v25
	v_readlane_b32 s5, v242, 22
	v_mov_b32_dpp v5, v27 quad_perm:[2,3,0,1] row_mask:0xf bank_mask:0xf
	v_cndmask_b32_e64 v5, v5, -v5, s[40:41]
	v_mov_b32_e32 v27, v5
	v_mov_b32_e32 v5, v129
	s_waitcnt vmcnt(3)
	v_mul_f32_e32 v0, v20, v0
	v_mov_b32_dpp v5, v24 quad_perm:[2,3,0,1] row_mask:0xf bank_mask:0xf
	v_cndmask_b32_e64 v38, v5, -v5, s[40:41]
	v_mov_b32_e32 v5, v129
	s_waitcnt vmcnt(1)
	v_mov_b32_e32 v10, v47
	v_mov_b32_e32 v47, v49
	v_mov_b32_dpp v5, v25 quad_perm:[2,3,0,1] row_mask:0xf bank_mask:0xf
	v_cndmask_b32_e64 v5, v5, -v5, s[40:41]
	v_mov_b32_e32 v25, v5
	v_mov_b32_e32 v5, v129
	v_pk_mul_f32 v[24:25], v[24:25], v[46:47]
	v_mov_b32_e32 v47, v23
	v_mov_b32_dpp v5, v22 quad_perm:[2,3,0,1] row_mask:0xf bank_mask:0xf
	v_cndmask_b32_e64 v46, v5, -v5, s[40:41]
	v_mov_b32_e32 v5, v129
	v_mov_b32_e32 v18, v29
	v_mov_b32_e32 v29, v31
	v_mov_b32_dpp v5, v23 quad_perm:[2,3,0,1] row_mask:0xf bank_mask:0xf
	v_cndmask_b32_e64 v5, v5, -v5, s[40:41]
	v_mov_b32_e32 v23, v5
	v_mov_b32_e32 v5, v129
	v_pk_mul_f32 v[22:23], v[22:23], v[28:29]
	v_mov_b32_e32 v28, v21
	v_mov_b32_dpp v5, v20 quad_perm:[2,3,0,1] row_mask:0xf bank_mask:0xf
	v_cndmask_b32_e64 v5, v5, -v5, s[40:41]
	v_mul_f32_e32 v20, v1, v5
	v_mov_b32_e32 v1, v129
	s_waitcnt vmcnt(0)
	v_mov_b32_e32 v6, v51
	v_mov_b32_e32 v51, v53
	v_mov_b32_dpp v1, v21 quad_perm:[2,3,0,1] row_mask:0xf bank_mask:0xf
	v_cndmask_b32_e64 v29, v1, -v1, s[40:41]
	v_pk_mul_f32 v[2:3], v[28:29], v[2:3]
	v_mov_b32_e32 v7, v52
	v_mov_b32_e32 v11, v48
	v_mov_b32_e32 v19, v30
	v_pk_mul_f32 v[26:27], v[26:27], v[50:51]
	v_mov_b32_e32 v1, v2
	v_mov_b32_e32 v21, v3
	v_pk_fma_f32 v[26:27], v[6:7], v[32:33], v[26:27]
	v_pk_fma_f32 v[24:25], v[10:11], v[38:39], v[24:25]
	v_pk_fma_f32 v[22:23], v[18:19], v[46:47], v[22:23]
	v_pk_add_f32 v[20:21], v[0:1], v[20:21]
.LBB0_498:
	v_pk_mul_f32 v[0:1], v[26:27], s[10:11] op_sel_hi:[1,0]
	v_pk_mul_f32 v[2:3], v[24:25], s[10:11] op_sel_hi:[1,0]
	v_pk_mul_f32 v[6:7], v[22:23], s[10:11] op_sel_hi:[1,0]
	v_pk_mul_f32 v[10:11], v[20:21], s[10:11] op_sel_hi:[1,0]
	v_cvt_pk_bf16_f32 v0, v0, v1
	v_cvt_pk_bf16_f32 v1, v2, v3
	v_cvt_pk_bf16_f32 v2, v6, v7
	v_cvt_pk_bf16_f32 v3, v10, v11
	v_mov_b32_e32 v15, v129
	global_store_dwordx4 v[8:9], v[0:3], off offset:768
	s_mov_b64 s[4:5], 0x2600
	s_nop 0
	v_lshl_add_u64 v[0:1], v[16:17], 0, v[14:15]
	v_lshl_add_u64 v[6:7], v[0:1], 0, s[4:5]
	s_movk_i32 s4, 0x2000
	v_add_co_u32_e32 v0, vcc, s4, v0
	v_readlane_b32 s4, v238, 46
	s_nop 0
	v_addc_co_u32_e32 v1, vcc, 0, v1, vcc
	global_load_dwordx4 v[0:3], v[0:1], off offset:1536
	s_nop 0
	global_load_dwordx4 v[6:9], v[6:7], off offset:16
	v_readlane_b32 s5, v238, 47
	s_nop 4
	global_load_dwordx4 v[16:19], v4, s[4:5] offset:16
	global_load_dwordx4 v[20:23], v4, s[4:5]
	s_mov_b64 s[4:5], -1
	s_waitcnt vmcnt(3)
	v_pk_mul_f32 v[4:5], v[0:1], v[0:1]
	v_pk_mul_f32 v[10:11], v[2:3], v[2:3]
	v_add_f32_e32 v4, v4, v5
	v_add_f32_e32 v4, v4, v10
	s_waitcnt vmcnt(2)
	v_pk_mul_f32 v[24:25], v[6:7], v[6:7]
	v_add_f32_e32 v4, v4, v11
	v_add_f32_e32 v4, v4, v24
	v_pk_mul_f32 v[26:27], v[8:9], v[8:9]
	v_add_f32_e32 v4, v4, v25
	v_add_f32_e32 v4, v4, v26
	v_add_f32_e32 v4, v4, v27
	s_nop 1
	v_add_f32_dpp v4, v4, v4 quad_perm:[1,0,3,2] row_mask:0xf bank_mask:0xf bound_ctrl:1
	s_nop 1
	v_add_f32_dpp v4, v4, v4 quad_perm:[2,3,0,1] row_mask:0xf bank_mask:0xf bound_ctrl:1
	s_nop 1
	v_add_f32_dpp v4, v4, v4 row_half_mirror row_mask:0xf bank_mask:0xf bound_ctrl:1
	v_fmamk_f32 v4, v4, 0x3c800000, v179
	v_cmp_gt_f32_e32 vcc, s60, v4
	v_mul_f32_e32 v5, 0x4b800000, v4
	s_nop 0
	v_cndmask_b32_e32 v4, v4, v5, vcc
	v_rsq_f32_e32 v4, v4
	s_nop 0
	v_mul_f32_e32 v5, 0x45800000, v4
	v_cndmask_b32_e32 v10, v4, v5, vcc
	v_pk_mul_f32 v[0:1], v[0:1], v[10:11] op_sel_hi:[1,0]
	v_pk_mul_f32 v[2:3], v[2:3], v[10:11] op_sel_hi:[1,0]
	v_pk_mul_f32 v[4:5], v[6:7], v[10:11] op_sel_hi:[1,0]
	v_pk_mul_f32 v[6:7], v[8:9], v[10:11] op_sel_hi:[1,0]
	s_waitcnt vmcnt(0)
	v_pk_mul_f32 v[0:1], v[20:21], v[0:1]
	v_pk_mul_f32 v[2:3], v[22:23], v[2:3]
	v_pk_mul_f32 v[4:5], v[16:17], v[4:5]
	v_pk_mul_f32 v[6:7], v[18:19], v[6:7]
	s_and_b64 vcc, exec, s[64:65]
	s_cbranch_vccz .LBB0_500
	v_cmp_gt_u32_e32 vcc, 32, v34
	v_readlane_b32 s4, v242, 21
	v_readlane_b32 s6, v242, 23
	v_cndmask_b32_e32 v8, v36, v35, vcc
	v_lshl_or_b32 v8, v8, 4, v37
	v_ashrrev_i32_e32 v9, 31, v8
	v_readlane_b32 s7, v242, 24
	v_mov_b32_e32 v15, v129
	v_mov_b32_e32 v30, v129
	v_lshl_add_u64 v[24:25], v[8:9], 3, s[6:7]
	v_mov_b64_e32 v[8:9], v[204:205]
	v_mov_b64_e32 v[10:11], v[206:207]
	v_mov_b64_e32 v[16:17], v[208:209]
	v_mov_b64_e32 v[18:19], v[210:211]
	v_mov_b64_e32 v[20:21], v[212:213]
	v_mov_b64_e32 v[22:23], v[214:215]
	s_nop 0
	v_mov_b64_e32 v[24:25], v[216:217]
	v_mov_b64_e32 v[26:27], v[218:219]
	v_mov_b32_dpp v15, v0 quad_perm:[2,3,0,1] row_mask:0xf bank_mask:0xf
	v_mov_b32_dpp v30, v1 quad_perm:[2,3,0,1] row_mask:0xf bank_mask:0xf
	v_cndmask_b32_e64 v31, v30, -v30, s[40:41]
	v_cndmask_b32_e64 v30, v15, -v15, s[40:41]
	v_mov_b32_e32 v15, v129
	v_readlane_b32 s5, v242, 22
	s_mov_b64 s[4:5], 0
	v_mov_b32_dpp v15, v2 quad_perm:[2,3,0,1] row_mask:0xf bank_mask:0xf
	s_waitcnt vmcnt(0)
	v_mov_b32_e32 v29, v26
	v_mov_b32_e32 v26, v25
	v_mov_b32_e32 v28, v24
	v_pk_mul_f32 v[24:25], v[26:27], v[30:31]
	v_mov_b32_e32 v30, v129
	v_mov_b32_e32 v27, v22
	v_mov_b32_e32 v22, v21
	v_mov_b32_dpp v30, v3 quad_perm:[2,3,0,1] row_mask:0xf bank_mask:0xf
	v_cndmask_b32_e64 v31, v30, -v30, s[40:41]
	v_cndmask_b32_e64 v30, v15, -v15, s[40:41]
	v_mov_b32_e32 v26, v20
	v_pk_mul_f32 v[20:21], v[22:23], v[30:31]
	v_mov_b32_e32 v15, v129
	v_mov_b32_e32 v30, v129
	v_mov_b32_e32 v23, v18
	v_mov_b32_dpp v15, v4 quad_perm:[2,3,0,1] row_mask:0xf bank_mask:0xf
	v_mov_b32_dpp v30, v5 quad_perm:[2,3,0,1] row_mask:0xf bank_mask:0xf
	v_cndmask_b32_e64 v31, v30, -v30, s[40:41]
	v_cndmask_b32_e64 v30, v15, -v15, s[40:41]
	v_mov_b32_e32 v15, v129
	v_mov_b32_e32 v18, v17
	v_mov_b32_e32 v22, v16
	v_mov_b32_dpp v15, v6 quad_perm:[2,3,0,1] row_mask:0xf bank_mask:0xf
	v_pk_mul_f32 v[16:17], v[18:19], v[30:31]
	v_mul_f32_e32 v18, v6, v8
	v_cndmask_b32_e64 v8, v15, -v15, s[40:41]
	v_mul_f32_e32 v30, v9, v8
	v_mov_b32_e32 v8, v129
	v_pk_fma_f32 v[16:17], v[4:5], v[22:23], v[16:17]
	s_nop 0
	v_mov_b32_dpp v8, v7 quad_perm:[2,3,0,1] row_mask:0xf bank_mask:0xf
	v_cndmask_b32_e64 v9, v8, -v8, s[40:41]
	v_mov_b32_e32 v8, v7
	v_pk_mul_f32 v[8:9], v[8:9], v[10:11]
	v_pk_fma_f32 v[10:11], v[2:3], v[26:27], v[20:21]
	v_mov_b32_e32 v19, v8
	v_mov_b32_e32 v31, v9
	v_pk_fma_f32 v[8:9], v[0:1], v[28:29], v[24:25]
	v_pk_add_f32 v[18:19], v[18:19], v[30:31]
